# prompt attention o-rescale: 32 v_pk_mul_f32 split into 64 v_mul_f32 (bit-identical)
# baseline (speedup 1.0000x reference)
.LBB0_1139:
	s_nop 6
	v_max_f32_e32 v145, v65, v65
	v_max_f32_e32 v173, v64, v64
	v_max_f32_e32 v145, v173, v145
	v_max3_f32 v145, v145, v66, v67
	v_max3_f32 v145, v145, v68, v69
	v_max3_f32 v145, v145, v70, v71
	v_max3_f32 v145, v145, v72, v73
	v_max3_f32 v145, v145, v74, v75
	v_max3_f32 v145, v145, v76, v77
	v_max3_f32 v145, v145, v78, v79
	v_mov_b32_e32 v173, v145
	s_nop 1
	v_permlane32_swap_b32_e32 v145, v173
	v_max3_f32 v145, v172, v145, v173
	v_sub_f32_e32 v64, v64, v145
	v_exp_f32_e32 v64, v64
	v_sub_f32_e32 v65, v65, v145
	v_exp_f32_e32 v65, v65
	v_sub_f32_e32 v66, v66, v145
	v_exp_f32_e32 v66, v66
	v_sub_f32_e32 v67, v67, v145
	v_exp_f32_e32 v67, v67
	v_sub_f32_e32 v68, v68, v145
	v_sub_f32_e32 v175, v172, v145
	v_add_f32_e32 v172, 0, v64
	v_exp_f32_e32 v68, v68
	v_sub_f32_e32 v69, v69, v145
	v_add_f32_e32 v172, v65, v172
	v_exp_f32_e32 v69, v69
	v_sub_f32_e32 v70, v70, v145
	v_add_f32_e32 v172, v66, v172
	v_exp_f32_e32 v70, v70
	v_sub_f32_e32 v71, v71, v145
	v_add_f32_e32 v172, v67, v172
	v_exp_f32_e32 v71, v71
	v_add_f32_e32 v172, v68, v172
	v_add_f32_e32 v172, v69, v172
	v_add_f32_e32 v172, v70, v172
	v_sub_f32_e32 v72, v72, v145
	v_add_f32_e32 v176, v71, v172
	v_exp_f32_e32 v172, v72
	v_sub_f32_e32 v72, v73, v145
	v_exp_f32_e32 v173, v72
	v_sub_f32_e32 v72, v74, v145
	v_exp_f32_e32 v174, v72
	v_sub_f32_e32 v72, v75, v145
	v_exp_f32_e32 v75, v72
	v_sub_f32_e32 v73, v76, v145
	v_add_f32_e32 v72, v172, v176
	v_exp_f32_e32 v76, v73
	v_sub_f32_e32 v73, v77, v145
	v_add_f32_e32 v72, v173, v72
	v_exp_f32_e32 v77, v73
	v_sub_f32_e32 v73, v78, v145
	v_add_f32_e32 v72, v174, v72
	v_exp_f32_e32 v78, v73
	v_sub_f32_e32 v73, v79, v145
	v_add_f32_e32 v72, v75, v72
	v_exp_f32_e32 v79, v73
	v_add_f32_e32 v72, v76, v72
	v_add_f32_e32 v72, v77, v72
	v_add_f32_e32 v72, v78, v72
	v_add_f32_e32 v73, v79, v72
	v_exp_f32_e32 v72, v175
	v_mov_b32_e32 v74, v73
	s_nop 1
	v_permlane32_swap_b32_e32 v73, v74
	v_cmp_neq_f32_e32 vcc, 1.0, v72
	s_cbranch_vccz .LBB0_1141
	v_mul_f32_e32 v62, v72, v62
	v_mul_f32_e32 v63, v72, v63
	v_mul_f32_e32 v60, v72, v60
	v_mul_f32_e32 v61, v72, v61
	v_mul_f32_e32 v58, v72, v58
	v_mul_f32_e32 v59, v72, v59
	v_mul_f32_e32 v56, v72, v56
	v_mul_f32_e32 v57, v72, v57
	v_mul_f32_e32 v54, v72, v54
	v_mul_f32_e32 v55, v72, v55
	v_mul_f32_e32 v52, v72, v52
	v_mul_f32_e32 v53, v72, v53
	v_mul_f32_e32 v50, v72, v50
	v_mul_f32_e32 v51, v72, v51
	v_mul_f32_e32 v48, v72, v48
	v_mul_f32_e32 v49, v72, v49
	v_mul_f32_e32 v46, v72, v46
	v_mul_f32_e32 v47, v72, v47
	v_mul_f32_e32 v44, v72, v44
	v_mul_f32_e32 v45, v72, v45
	v_mul_f32_e32 v42, v72, v42
	v_mul_f32_e32 v43, v72, v43
	v_mul_f32_e32 v40, v72, v40
	v_mul_f32_e32 v41, v72, v41
	v_mul_f32_e32 v38, v72, v38
	v_mul_f32_e32 v39, v72, v39
	v_mul_f32_e32 v36, v72, v36
	v_mul_f32_e32 v37, v72, v37
	v_mul_f32_e32 v34, v72, v34
	v_mul_f32_e32 v35, v72, v35
	v_mul_f32_e32 v32, v72, v32
	v_mul_f32_e32 v33, v72, v33
	v_mul_f32_e32 v30, v72, v30
	v_mul_f32_e32 v31, v72, v31
	v_mul_f32_e32 v28, v72, v28
	v_mul_f32_e32 v29, v72, v29
	v_mul_f32_e32 v26, v72, v26
	v_mul_f32_e32 v27, v72, v27
	v_mul_f32_e32 v24, v72, v24
	v_mul_f32_e32 v25, v72, v25
	v_mul_f32_e32 v22, v72, v22
	v_mul_f32_e32 v23, v72, v23
	v_mul_f32_e32 v20, v72, v20
	v_mul_f32_e32 v21, v72, v21
	v_mul_f32_e32 v18, v72, v18
	v_mul_f32_e32 v19, v72, v19
	v_mul_f32_e32 v16, v72, v16
	v_mul_f32_e32 v17, v72, v17
	v_mul_f32_e32 v14, v72, v14
	v_mul_f32_e32 v15, v72, v15
	v_mul_f32_e32 v12, v72, v12
	v_mul_f32_e32 v13, v72, v13
	v_mul_f32_e32 v10, v72, v10
	v_mul_f32_e32 v11, v72, v11
	v_mul_f32_e32 v8, v72, v8
	v_mul_f32_e32 v9, v72, v9
	v_mul_f32_e32 v6, v72, v6
	v_mul_f32_e32 v7, v72, v7
	v_mul_f32_e32 v4, v72, v4
	v_mul_f32_e32 v5, v72, v5
	v_mul_f32_e32 v2, v72, v2
	v_mul_f32_e32 v3, v72, v3
	v_mul_f32_e32 v0, v72, v0
	v_mul_f32_e32 v1, v72, v1
